# attention unit prologue: the four serial rope-table load pairs issued together at the first pair (three exposed waits removed per unit)
# speedup vs baseline: 1.0046x; 1.0014x over previous
.LBB0_952:
	s_mov_b64 s[6:7], s[0:1]
	s_load_dwordx2 s[6:7], s[6:7], 0xa8
	s_mul_i32 s5, s24, 0x1800
	s_mov_b64 s[26:27], s[0:1]
	s_movk_i32 s19, 0x1800
	s_waitcnt lgkmcnt(0)
	s_add_u32 s5, s6, s5
	s_mul_i32 s6, s44, 0xc0
	s_addc_u32 s8, s7, 0
	s_ashr_i32 s7, s6, 31
	s_lshl_b64 s[6:7], s[6:7], 1
	s_add_u32 s6, s5, s6
	s_addc_u32 s7, s8, s7
	s_mov_b64 s[8:9], s[0:1]
	s_load_dwordx2 s[10:11], s[8:9], 0xa8
	s_mov_b64 s[8:9], s[0:1]
	s_load_dwordx2 s[8:9], s[8:9], 0xa8
	s_load_dwordx2 s[30:31], s[26:27], 0xa8
	s_mov_b64 s[26:27], s[0:1]
	s_load_dwordx2 s[26:27], s[26:27], 0xa8
	v_mbcnt_lo_u32_b32 v62, -1, 0
	v_mbcnt_hi_u32_b32 v62, -1, v62
	v_readlane_b32 s5, v254, 20
	v_ashrrev_i32_e32 v64, 4, v62
	v_lshlrev_b32_e32 v48, 3, v64
	v_ashrrev_i32_e32 v49, 31, v48
	v_and_b32_e32 v63, 15, v62
	v_lshl_add_u64 v[0:1], v[48:49], 1, s[6:7]
	s_mov_b64 s[6:7], 0x34800000
	v_or_b32_e32 v2, s5, v63
	v_lshl_add_u64 v[0:1], v[0:1], 0, s[6:7]
	v_mad_u64_u32 v[4:5], s[6:7], v2, s19, v[0:1]
	v_or_b32_e32 v2, 16, v2
	v_mad_u64_u32 v[0:1], s[6:7], v2, s19, v[0:1]
	global_load_dwordx4 v[20:23], v[4:5], off offset:320
	global_load_dwordx4 v[40:43], v[0:1], off
	global_load_dwordx4 v[36:39], v[0:1], off offset:64
	global_load_dwordx4 v[28:31], v[0:1], off offset:128
	global_load_dwordx4 v[24:27], v[0:1], off offset:192
	global_load_dwordx4 v[32:35], v[0:1], off offset:256
	global_load_dwordx4 v[44:47], v[0:1], off offset:320
	v_or_b32_e32 v0, s4, v63
	v_add_u32_e32 v50, s5, v0
	global_load_dwordx4 v[0:3], v[4:5], off
	global_load_dwordx4 v[52:55], v[4:5], off offset:64
	global_load_dwordx4 v[12:15], v[4:5], off offset:128
	global_load_dwordx4 v[8:11], v[4:5], off offset:192
	global_load_dwordx4 v[16:19], v[4:5], off offset:256
	s_mov_b32 s4, 0x3dd53b94
	s_cmp_lg_u64 s[28:29], 0
	s_cselect_b64 s[34:35], -1, 0
	s_cmp_eq_u64 s[28:29], 0
	s_waitcnt vmcnt(0)
	v_and_b32_e32 v51, 0xffff0000, v55
	v_mul_f32_e32 v51, 0x3dd53b94, v51
	v_lshlrev_b32_e32 v6, 16, v0
	v_and_b32_e32 v0, 0xffff0000, v0
	v_mul_f32_e32 v0, 0x3dd53b94, v0
	v_mul_f32_e32 v6, 0x3dd53b94, v6
	v_cvt_pk_bf16_f32 v4, v6, v0
	v_lshlrev_b32_e32 v0, 16, v1
	v_and_b32_e32 v1, 0xffff0000, v1
	v_mul_f32_e32 v0, 0x3dd53b94, v0
	v_mul_f32_e32 v1, 0x3dd53b94, v1
	v_cvt_pk_bf16_f32 v5, v0, v1
	v_lshlrev_b32_e32 v0, 16, v2
	v_and_b32_e32 v1, 0xffff0000, v2
	v_mul_f32_e32 v0, 0x3dd53b94, v0
	v_mul_f32_e32 v1, 0x3dd53b94, v1
	v_cvt_pk_bf16_f32 v6, v0, v1
	v_lshlrev_b32_e32 v0, 16, v3
	v_and_b32_e32 v1, 0xffff0000, v3
	v_mul_f32_e32 v0, 0x3dd53b94, v0
	v_mul_f32_e32 v1, 0x3dd53b94, v1
	v_cvt_pk_bf16_f32 v7, v0, v1
	v_lshlrev_b32_e32 v0, 16, v52
	v_and_b32_e32 v1, 0xffff0000, v52
	v_mul_f32_e32 v0, 0x3dd53b94, v0
	v_mul_f32_e32 v1, 0x3dd53b94, v1
	v_cvt_pk_bf16_f32 v0, v0, v1
	v_lshlrev_b32_e32 v1, 16, v53
	v_and_b32_e32 v2, 0xffff0000, v53
	v_mul_f32_e32 v1, 0x3dd53b94, v1
	v_mul_f32_e32 v2, 0x3dd53b94, v2
	v_cvt_pk_bf16_f32 v1, v1, v2
	v_lshlrev_b32_e32 v2, 16, v54
	v_and_b32_e32 v3, 0xffff0000, v54
	v_mul_f32_e32 v2, 0x3dd53b94, v2
	v_mul_f32_e32 v3, 0x3dd53b94, v3
	v_cvt_pk_bf16_f32 v2, v2, v3
	v_lshlrev_b32_e32 v3, 16, v55
	v_mul_f32_e32 v3, 0x3dd53b94, v3
	v_cvt_pk_bf16_f32 v3, v3, v51
	v_lshlrev_b32_e32 v51, 16, v12
	v_and_b32_e32 v12, 0xffff0000, v12
	v_mul_f32_e32 v51, 0x3dd53b94, v51
	v_mul_f32_e32 v12, 0x3dd53b94, v12
	v_cvt_pk_bf16_f32 v12, v51, v12
	v_lshlrev_b32_e32 v51, 16, v13
	v_and_b32_e32 v13, 0xffff0000, v13
	v_mul_f32_e32 v51, 0x3dd53b94, v51
	v_mul_f32_e32 v13, 0x3dd53b94, v13
	v_cvt_pk_bf16_f32 v13, v51, v13
	v_lshlrev_b32_e32 v51, 16, v14
	v_and_b32_e32 v14, 0xffff0000, v14
	v_mul_f32_e32 v51, 0x3dd53b94, v51
	v_mul_f32_e32 v14, 0x3dd53b94, v14
	v_cvt_pk_bf16_f32 v14, v51, v14
	v_lshlrev_b32_e32 v51, 16, v15
	v_and_b32_e32 v15, 0xffff0000, v15
	v_mul_f32_e32 v51, 0x3dd53b94, v51
	v_mul_f32_e32 v15, 0x3dd53b94, v15
	v_cvt_pk_bf16_f32 v15, v51, v15
	v_lshlrev_b32_e32 v51, 16, v8
	v_and_b32_e32 v8, 0xffff0000, v8
	v_mul_f32_e32 v51, 0x3dd53b94, v51
	v_mul_f32_e32 v8, 0x3dd53b94, v8
	v_cvt_pk_bf16_f32 v8, v51, v8
	v_lshlrev_b32_e32 v51, 16, v9
	v_and_b32_e32 v9, 0xffff0000, v9
	v_mul_f32_e32 v51, 0x3dd53b94, v51
	v_mul_f32_e32 v9, 0x3dd53b94, v9
	v_cvt_pk_bf16_f32 v9, v51, v9
	v_lshlrev_b32_e32 v51, 16, v10
	v_and_b32_e32 v10, 0xffff0000, v10
	v_mul_f32_e32 v51, 0x3dd53b94, v51
	v_mul_f32_e32 v10, 0x3dd53b94, v10
	v_cvt_pk_bf16_f32 v10, v51, v10
	v_lshlrev_b32_e32 v51, 16, v11
	v_and_b32_e32 v11, 0xffff0000, v11
	v_mul_f32_e32 v51, 0x3dd53b94, v51
	v_mul_f32_e32 v11, 0x3dd53b94, v11
	v_cvt_pk_bf16_f32 v11, v51, v11
	v_ashrrev_i32_e32 v51, 31, v50
	v_lshlrev_b64 v[52:53], 8, v[50:51]
	v_lshlrev_b32_e32 v55, 16, v16
	v_lshlrev_b32_e32 v54, 16, v17
	v_and_b32_e32 v57, 0xffff0000, v16
	v_and_b32_e32 v56, 0xffff0000, v17
	v_lshl_add_u64 v[52:53], s[28:29], 0, v[52:53]
	v_pk_mul_f32 v[60:61], v[54:55], s[4:5] op_sel_hi:[1,0]
	v_pk_mul_f32 v[54:55], v[56:57], s[4:5] op_sel_hi:[1,0]
	v_lshlrev_b32_e32 v17, 16, v18
	v_lshlrev_b32_e32 v16, 16, v19
	v_and_b32_e32 v57, 0xffff0000, v18
	v_and_b32_e32 v56, 0xffff0000, v19
	v_pk_mul_f32 v[58:59], v[16:17], s[4:5] op_sel_hi:[1,0]
	v_pk_mul_f32 v[56:57], v[56:57], s[4:5] op_sel_hi:[1,0]
	v_lshl_add_u64 v[52:53], v[48:49], 2, v[52:53]
	s_cbranch_scc1 .LBB0_954
	global_load_dwordx4 v[16:19], v[52:53], off offset:16
	global_load_dwordx4 v[66:69], v[52:53], off
	v_add_co_u32_e32 v124, vcc, 0x1000, v52
	global_load_dwordx4 v[100:103], v[52:53], off offset:144
	global_load_dwordx4 v[104:107], v[52:53], off offset:128
	v_addc_co_u32_e32 v125, vcc, 0, v53, vcc
	global_load_dwordx4 v[108:111], v[124:125], off offset:16
	global_load_dwordx4 v[112:115], v[124:125], off
	global_load_dwordx4 v[116:119], v[124:125], off offset:144
	global_load_dwordx4 v[120:123], v[124:125], off offset:128
	s_waitcnt vmcnt(6)
	v_mov_b32_e32 v71, v66
	v_mov_b32_e32 v66, v69
	v_mov_b32_e32 v70, v68
	v_pk_mul_f32 v[68:69], v[54:55], v[66:67]
	s_nop 0
	v_pk_fma_f32 v[68:69], v[60:61], v[70:71], v[68:69] neg_lo:[0,0,1] neg_hi:[0,0,1]
	v_pk_mul_f32 v[60:61], v[60:61], v[66:67]
	s_nop 0
	v_pk_fma_f32 v[54:55], v[54:55], v[70:71], v[60:61]
	v_mov_b32_e32 v61, v16
	v_mov_b32_e32 v16, v19
	v_mov_b32_e32 v60, v18
	v_pk_mul_f32 v[18:19], v[56:57], v[16:17]
	v_pk_mul_f32 v[16:17], v[58:59], v[16:17]
	v_pk_fma_f32 v[18:19], v[58:59], v[60:61], v[18:19] neg_lo:[0,0,1] neg_hi:[0,0,1]
	v_pk_fma_f32 v[56:57], v[56:57], v[60:61], v[16:17]
	v_mov_b64_e32 v[58:59], v[18:19]
	v_mov_b64_e32 v[60:61], v[68:69]
.LBB0_954:
	v_cvt_pk_bf16_f32 v16, v61, v55
	v_cvt_pk_bf16_f32 v17, v60, v54
	v_cvt_pk_bf16_f32 v18, v59, v57
	v_cvt_pk_bf16_f32 v19, v58, v56
	v_lshlrev_b32_e32 v55, 16, v20
	v_lshlrev_b32_e32 v54, 16, v21
	v_and_b32_e32 v57, 0xffff0000, v20
	v_and_b32_e32 v56, 0xffff0000, v21
	v_lshlrev_b32_e32 v21, 16, v22
	v_lshlrev_b32_e32 v20, 16, v23
	v_pk_mul_f32 v[60:61], v[54:55], s[4:5] op_sel_hi:[1,0]
	v_pk_mul_f32 v[54:55], v[56:57], s[4:5] op_sel_hi:[1,0]
	v_and_b32_e32 v57, 0xffff0000, v22
	v_and_b32_e32 v56, 0xffff0000, v23
	v_pk_mul_f32 v[58:59], v[20:21], s[4:5] op_sel_hi:[1,0]
	v_cndmask_b32_e64 v20, 0, 1, s[34:35]
	v_cmp_ne_u32_e64 s[6:7], 1, v20
	s_andn2_b64 vcc, exec, s[34:35]
	v_pk_mul_f32 v[56:57], v[56:57], s[4:5] op_sel_hi:[1,0]
	s_cbranch_vccnz .LBB0_956
	s_waitcnt vmcnt(4)
	v_mov_b64_e32 v[20:21], v[100:101]
	v_mov_b64_e32 v[22:23], v[102:103]
	v_mov_b64_e32 v[66:67], v[104:105]
	v_mov_b64_e32 v[68:69], v[106:107]
	v_mov_b32_e32 v53, v66
	v_mov_b32_e32 v66, v69
	v_mov_b32_e32 v52, v68
	v_pk_mul_f32 v[68:69], v[54:55], v[66:67]
	s_nop 0
	v_pk_fma_f32 v[68:69], v[60:61], v[52:53], v[68:69] neg_lo:[0,0,1] neg_hi:[0,0,1]
	v_pk_mul_f32 v[60:61], v[60:61], v[66:67]
	s_nop 0
	v_pk_fma_f32 v[54:55], v[54:55], v[52:53], v[60:61]
	v_mov_b32_e32 v53, v20
	v_mov_b32_e32 v20, v23
	v_mov_b32_e32 v52, v22
	v_pk_mul_f32 v[22:23], v[56:57], v[20:21]
	v_pk_mul_f32 v[20:21], v[58:59], v[20:21]
	v_pk_fma_f32 v[22:23], v[58:59], v[52:53], v[22:23] neg_lo:[0,0,1] neg_hi:[0,0,1]
	v_pk_fma_f32 v[56:57], v[56:57], v[52:53], v[20:21]
	v_mov_b64_e32 v[58:59], v[22:23]
	v_mov_b64_e32 v[60:61], v[68:69]
.LBB0_956:
	v_lshlrev_b32_e32 v51, 16, v40
	v_and_b32_e32 v40, 0xffff0000, v40
	v_mul_f32_e32 v51, 0x3dd53b94, v51
	v_mul_f32_e32 v40, 0x3dd53b94, v40
	v_cvt_pk_bf16_f32 v20, v61, v55
	v_cvt_pk_bf16_f32 v21, v60, v54
	v_cvt_pk_bf16_f32 v22, v59, v57
	v_cvt_pk_bf16_f32 v23, v58, v56
	v_cvt_pk_bf16_f32 v40, v51, v40
	v_lshlrev_b32_e32 v51, 16, v41
	v_and_b32_e32 v41, 0xffff0000, v41
	v_mul_f32_e32 v51, 0x3dd53b94, v51
	v_mul_f32_e32 v41, 0x3dd53b94, v41
	v_cvt_pk_bf16_f32 v41, v51, v41
	v_lshlrev_b32_e32 v51, 16, v42
	v_and_b32_e32 v42, 0xffff0000, v42
	v_mul_f32_e32 v51, 0x3dd53b94, v51
	v_mul_f32_e32 v42, 0x3dd53b94, v42
	v_cvt_pk_bf16_f32 v42, v51, v42
	v_lshlrev_b32_e32 v51, 16, v43
	v_and_b32_e32 v43, 0xffff0000, v43
	v_mul_f32_e32 v51, 0x3dd53b94, v51
	v_mul_f32_e32 v43, 0x3dd53b94, v43
	v_cvt_pk_bf16_f32 v43, v51, v43
	v_lshlrev_b32_e32 v51, 16, v36
	v_and_b32_e32 v36, 0xffff0000, v36
	v_mul_f32_e32 v51, 0x3dd53b94, v51
	v_mul_f32_e32 v36, 0x3dd53b94, v36
	v_cvt_pk_bf16_f32 v36, v51, v36
	v_lshlrev_b32_e32 v51, 16, v37
	v_and_b32_e32 v37, 0xffff0000, v37
	v_mul_f32_e32 v51, 0x3dd53b94, v51
	v_mul_f32_e32 v37, 0x3dd53b94, v37
	v_cvt_pk_bf16_f32 v37, v51, v37
	v_lshlrev_b32_e32 v51, 16, v38
	v_and_b32_e32 v38, 0xffff0000, v38
	v_mul_f32_e32 v51, 0x3dd53b94, v51
	v_mul_f32_e32 v38, 0x3dd53b94, v38
	v_cvt_pk_bf16_f32 v38, v51, v38
	v_lshlrev_b32_e32 v51, 16, v39
	v_and_b32_e32 v39, 0xffff0000, v39
	v_mul_f32_e32 v51, 0x3dd53b94, v51
	v_mul_f32_e32 v39, 0x3dd53b94, v39
	v_cvt_pk_bf16_f32 v39, v51, v39
	v_lshlrev_b32_e32 v51, 16, v28
	v_and_b32_e32 v28, 0xffff0000, v28
	v_mul_f32_e32 v51, 0x3dd53b94, v51
	v_mul_f32_e32 v28, 0x3dd53b94, v28
	v_cvt_pk_bf16_f32 v28, v51, v28
	v_lshlrev_b32_e32 v51, 16, v29
	v_and_b32_e32 v29, 0xffff0000, v29
	v_mul_f32_e32 v51, 0x3dd53b94, v51
	v_mul_f32_e32 v29, 0x3dd53b94, v29
	v_cvt_pk_bf16_f32 v29, v51, v29
	v_lshlrev_b32_e32 v51, 16, v30
	v_and_b32_e32 v30, 0xffff0000, v30
	v_mul_f32_e32 v51, 0x3dd53b94, v51
	v_mul_f32_e32 v30, 0x3dd53b94, v30
	v_cvt_pk_bf16_f32 v30, v51, v30
	v_lshlrev_b32_e32 v51, 16, v31
	v_and_b32_e32 v31, 0xffff0000, v31
	v_mul_f32_e32 v51, 0x3dd53b94, v51
	v_mul_f32_e32 v31, 0x3dd53b94, v31
	v_cvt_pk_bf16_f32 v31, v51, v31
	v_lshlrev_b32_e32 v51, 16, v24
	v_and_b32_e32 v24, 0xffff0000, v24
	v_mul_f32_e32 v51, 0x3dd53b94, v51
	v_mul_f32_e32 v24, 0x3dd53b94, v24
	v_cvt_pk_bf16_f32 v24, v51, v24
	v_lshlrev_b32_e32 v51, 16, v25
	v_and_b32_e32 v25, 0xffff0000, v25
	v_mul_f32_e32 v51, 0x3dd53b94, v51
	v_mul_f32_e32 v25, 0x3dd53b94, v25
	v_cvt_pk_bf16_f32 v25, v51, v25
	v_lshlrev_b32_e32 v51, 16, v26
	v_and_b32_e32 v26, 0xffff0000, v26
	v_mul_f32_e32 v51, 0x3dd53b94, v51
	v_mul_f32_e32 v26, 0x3dd53b94, v26
	v_cvt_pk_bf16_f32 v26, v51, v26
	v_lshlrev_b32_e32 v51, 16, v27
	v_and_b32_e32 v27, 0xffff0000, v27
	v_mul_f32_e32 v51, 0x3dd53b94, v51
	v_mul_f32_e32 v27, 0x3dd53b94, v27
	v_or_b32_e32 v50, 16, v50
	v_cvt_pk_bf16_f32 v27, v51, v27
	v_ashrrev_i32_e32 v51, 31, v50
	v_lshlrev_b64 v[50:51], 8, v[50:51]
	v_lshl_add_u64 v[54:55], s[28:29], 0, v[50:51]
	v_lshlrev_b32_e32 v51, 16, v32
	v_lshlrev_b32_e32 v50, 16, v33
	v_and_b32_e32 v53, 0xffff0000, v32
	v_and_b32_e32 v52, 0xffff0000, v33
	v_pk_mul_f32 v[58:59], v[50:51], s[4:5] op_sel_hi:[1,0]
	v_pk_mul_f32 v[50:51], v[52:53], s[4:5] op_sel_hi:[1,0]
	v_lshlrev_b32_e32 v33, 16, v34
	v_lshlrev_b32_e32 v32, 16, v35
	v_and_b32_e32 v53, 0xffff0000, v34
	v_and_b32_e32 v52, 0xffff0000, v35
	v_pk_mul_f32 v[56:57], v[32:33], s[4:5] op_sel_hi:[1,0]
	v_pk_mul_f32 v[52:53], v[52:53], s[4:5] op_sel_hi:[1,0]
	s_and_b64 vcc, exec, s[6:7]
	v_lshl_add_u64 v[54:55], v[48:49], 2, v[54:55]
	s_cbranch_vccnz .LBB0_958
	s_waitcnt vmcnt(2)
	v_mov_b64_e32 v[32:33], v[108:109]
	v_mov_b64_e32 v[34:35], v[110:111]
	v_mov_b64_e32 v[66:67], v[112:113]
	v_mov_b64_e32 v[68:69], v[114:115]
	v_mov_b32_e32 v49, v66
	v_mov_b32_e32 v66, v69
	v_mov_b32_e32 v48, v68
	v_pk_mul_f32 v[60:61], v[50:51], v[66:67]
	s_nop 0
	v_pk_fma_f32 v[60:61], v[58:59], v[48:49], v[60:61] neg_lo:[0,0,1] neg_hi:[0,0,1]
	v_pk_mul_f32 v[58:59], v[58:59], v[66:67]
	s_nop 0
	v_pk_fma_f32 v[50:51], v[50:51], v[48:49], v[58:59]
	v_mov_b32_e32 v49, v32
	v_mov_b32_e32 v32, v35
	v_mov_b32_e32 v48, v34
	v_pk_mul_f32 v[34:35], v[52:53], v[32:33]
	v_pk_mul_f32 v[32:33], v[56:57], v[32:33]
	v_pk_fma_f32 v[34:35], v[56:57], v[48:49], v[34:35] neg_lo:[0,0,1] neg_hi:[0,0,1]
	v_pk_fma_f32 v[52:53], v[52:53], v[48:49], v[32:33]
	v_mov_b64_e32 v[56:57], v[34:35]
	v_mov_b64_e32 v[58:59], v[60:61]
.LBB0_958:
	v_cvt_pk_bf16_f32 v32, v59, v51
	v_cvt_pk_bf16_f32 v33, v58, v50
	v_lshlrev_b32_e32 v49, 16, v44
	v_lshlrev_b32_e32 v48, 16, v45
	v_and_b32_e32 v51, 0xffff0000, v44
	v_and_b32_e32 v50, 0xffff0000, v45
	v_cvt_pk_bf16_f32 v34, v57, v53
	v_cvt_pk_bf16_f32 v35, v56, v52
	v_pk_mul_f32 v[56:57], v[48:49], s[4:5] op_sel_hi:[1,0]
	v_pk_mul_f32 v[48:49], v[50:51], s[4:5] op_sel_hi:[1,0]
	v_lshlrev_b32_e32 v45, 16, v46
	v_lshlrev_b32_e32 v44, 16, v47
	v_and_b32_e32 v51, 0xffff0000, v46
	v_and_b32_e32 v50, 0xffff0000, v47
	v_pk_mul_f32 v[52:53], v[44:45], s[4:5] op_sel_hi:[1,0]
	s_and_b64 vcc, exec, s[6:7]
	v_pk_mul_f32 v[50:51], v[50:51], s[4:5] op_sel_hi:[1,0]
	s_cbranch_vccnz .LBB0_960
	s_waitcnt vmcnt(0)
	v_mov_b64_e32 v[44:45], v[116:117]
	v_mov_b64_e32 v[46:47], v[118:119]
	v_mov_b64_e32 v[58:59], v[120:121]
	v_mov_b64_e32 v[60:61], v[122:123]
	v_mov_b32_e32 v55, v58
	v_mov_b32_e32 v58, v61
	v_mov_b32_e32 v54, v60
	v_pk_mul_f32 v[60:61], v[48:49], v[58:59]
	s_nop 0
	v_pk_fma_f32 v[60:61], v[56:57], v[54:55], v[60:61] neg_lo:[0,0,1] neg_hi:[0,0,1]
	v_pk_mul_f32 v[56:57], v[56:57], v[58:59]
	s_nop 0
	v_pk_fma_f32 v[48:49], v[48:49], v[54:55], v[56:57]
	v_mov_b32_e32 v55, v44
	v_mov_b32_e32 v44, v47
	v_mov_b32_e32 v54, v46
	v_pk_mul_f32 v[46:47], v[50:51], v[44:45]
	v_pk_mul_f32 v[44:45], v[52:53], v[44:45]
	v_pk_fma_f32 v[46:47], v[52:53], v[54:55], v[46:47] neg_lo:[0,0,1] neg_hi:[0,0,1]
	v_pk_fma_f32 v[50:51], v[50:51], v[54:55], v[44:45]
	v_mov_b64_e32 v[52:53], v[46:47]
	v_mov_b64_e32 v[56:57], v[60:61]
